# attn: K tile in LDS re-laid out as 256B rows with XOR swizzle on 16B chunks (conflict-free ds_read_b128 under the gfx950 lane grouping; was 2-way with the 272B padded rows)
# speedup vs baseline: 1.0129x; 1.0129x over previous
.Lch_skipB:
	s_lshl_b32 s18, s12, 7
	s_and_b32 s18, s18, 0x780
	s_add_i32 s18, s18, s2
	s_lshl_b32 s19, s19, 2
	v_readlane_b32 s52, v252, 25
	v_and_b32_e32 v165, 15, v100
	v_readlane_b32 s60, v252, 33
	v_readlane_b32 s61, v252, 34
	s_mov_b32 s9, s1
	v_bfe_u32 v43, v100, 4, 2
	v_lshlrev_b32_e32 v64, 4, v43
	v_add_u32_e32 v26, 0, v26
	v_lshlrev_b32_e32 v158, 3, v43
	v_mov_b32_e32 v0, s19
	s_add_i32 s19, s18, s15
	global_load_dword v44, v0, s[60:61] offset:480
	global_load_dword v45, v0, s[60:61] offset:992
	v_or_b32_e32 v2, s19, v165
	v_mov_b64_e32 v[0:1], s[4:5]
	v_mad_i64_i32 v[0:1], s[20:21], v2, s69, v[0:1]
	v_lshl_add_u64 v[0:1], v[0:1], 0, s[0:1]
	v_lshl_add_u64 v[0:1], v[0:1], 0, s[8:9]
	v_lshl_add_u64 v[0:1], v[0:1], 0, v[64:65]
	s_movk_i32 s0, 0x6000
	v_add_co_u32_e32 v8, vcc, s0, v0
	s_movk_i32 s0, 0x110
	s_mov_b64 s[8:9], 0x6000
	v_and_b32_e32 v46, 15, v161
	v_lshl_add_u64 v[12:13], v[0:1], 0, s[8:9]
	v_addc_co_u32_e32 v9, vcc, 0, v1, vcc
	v_xor_b32_e32 v46, v46, v165
	v_lshlrev_b32_e32 v46, 4, v46
	v_lshl_add_u32 v166, v161, 8, v46
	global_load_dwordx4 v[0:3], v[12:13], off offset:64
	global_load_dwordx4 v[4:7], v[12:13], off offset:128
	s_nop 0
	global_load_dwordx4 v[8:11], v[8:9], off
	s_nop 0
	global_load_dwordx4 v[12:15], v[12:13], off offset:192
	s_waitcnt vmcnt(0)
	s_cmp_lg_u32 s32, 0
	s_cbranch_scc1 .Lch_c1
	ds_write_b128 v166, v[18:21]
.Lch_c1:
	v_add_u32_e32 v167, 0x2000, v166
	s_waitcnt vmcnt(22)
	s_cmp_lg_u32 s32, 0
	s_cbranch_scc1 .Lch_c2
	ds_write_b128 v167, v[22:25]

.Lch_c3:
	v_readlane_b32 s8, v254, 60
	s_waitcnt vmcnt(15)
	v_mul_f32_e32 v173, 0x413504f3, v44
	s_waitcnt vmcnt(14)
	v_mul_f32_e32 v174, 0x413504f3, v45
	v_readlane_b32 s56, v252, 29
	v_readlane_b32 s57, v252, 30
	v_readlane_b32 s58, v252, 31
	v_readlane_b32 s59, v252, 32
	v_and_b32_e32 v27, 3, v165
	v_xor_b32_e32 v27, v27, v43
	v_lshlrev_b32_e32 v27, 4, v27
	v_lshl_add_u32 v27, v165, 8, v27
	v_lshrrev_b32_e32 v29, 2, v165
	v_xor_b32_e32 v177, 0, v29
	v_lshl_add_u32 v177, v177, 6, v27
	v_xor_b32_e32 v191, 1, v29
	v_lshl_add_u32 v191, v191, 6, v27
	v_xor_b32_e32 v163, 2, v29
	v_lshl_add_u32 v163, v163, 6, v27
	v_xor_b32_e32 v164, 3, v29
	v_lshl_add_u32 v164, v164, 6, v27
	s_cselect_b32 s0, 0, 0
	s_cmp_lg_u32 s8, -1
	s_cselect_b32 s8, s8, 0
	v_mov_b32_e32 v64, v65
	v_lshlrev_b32_e32 v30, 2, v43
	s_add_i32 s8, s0, 0x4400
	s_add_i32 s0, s0, 0x11800
	v_mov_b64_e32 v[36:37], v[64:65]
	v_mov_b64_e32 v[44:45], v[64:65]
	v_mov_b64_e32 v[52:53], v[64:65]
	v_mov_b64_e32 v[60:61], v[64:65]
	v_mov_b64_e32 v[70:71], v[66:67]
	v_mov_b64_e32 v[78:79], v[66:67]
	v_mov_b64_e32 v[86:87], v[66:67]
	v_mov_b64_e32 v[94:95], v[66:67]
	v_mov_b64_e32 v[32:33], v[64:65]
	v_mov_b64_e32 v[40:41], v[64:65]
	v_mov_b64_e32 v[48:49], v[64:65]
	v_mov_b64_e32 v[56:57], v[64:65]
	v_mov_b64_e32 v[74:75], v[66:67]
	v_mov_b64_e32 v[82:83], v[66:67]
	v_mov_b64_e32 v[90:91], v[66:67]
	v_mov_b64_e32 v[98:99], v[66:67]
	s_mov_b32 s29, 0x504000
	s_add_u32 s72, s24, s29
	s_addc_u32 s73, s25, 0
	s_add_u32 s74, s26, s29
	s_addc_u32 s75, s27, 0
	s_add_u32 s76, s74, 0xa0800
	s_addc_u32 s77, s75, 0
	s_add_u32 s78, s76, 0xa0800
	s_addc_u32 s79, s77, 0
	s_add_u32 s80, s78, 0xa0800
	s_addc_u32 s81, s79, 0
	s_mov_b32 s32, 1
	v_sub_u32_e32 v193, v30, v165
	s_mov_b32 s0, -2
	v_mov_b64_e32 v[38:39], v[66:67]
	v_mov_b64_e32 v[46:47], v[66:67]
	v_mov_b64_e32 v[54:55], v[66:67]
	v_mov_b64_e32 v[62:63], v[66:67]
	v_mov_b64_e32 v[68:69], v[64:65]
	v_mov_b64_e32 v[76:77], v[64:65]
	v_mov_b64_e32 v[84:85], v[64:65]
	v_mov_b64_e32 v[92:93], v[64:65]
	v_mov_b64_e32 v[34:35], v[66:67]
	v_mov_b64_e32 v[42:43], v[66:67]
	v_mov_b64_e32 v[50:51], v[66:67]
	v_mov_b64_e32 v[58:59], v[66:67]
	v_mov_b64_e32 v[72:73], v[64:65]
	v_mov_b64_e32 v[80:81], v[64:65]
	v_mov_b64_e32 v[88:89], v[64:65]
	v_mov_b64_e32 v[96:97], v[64:65]
	v_readlane_b32 s62, v252, 35
	v_readlane_b32 s63, v252, 36
	v_readlane_b32 s64, v252, 37
	v_readlane_b32 s65, v252, 38
	v_readlane_b32 s66, v252, 39
	v_readlane_b32 s67, v252, 40
.LBB0_252:
	ds_read_b128 v[100:103], v177 offset:0
	ds_read_b128 v[104:107], v191 offset:0
	ds_read_b128 v[108:111], v163 offset:0
	ds_read_b128 v[112:115], v164 offset:0
	ds_read_b128 v[116:119], v177 offset:4096
	ds_read_b128 v[120:123], v191 offset:4096
	ds_read_b128 v[124:127], v163 offset:4096
	ds_read_b128 v[128:131], v164 offset:4096
	global_load_dwordx4 v[206:209], v239, s[74:75]
	global_load_dwordx4 v[210:213], v239, s[76:77]
	global_load_dwordx4 v[214:217], v239, s[78:79]
	global_load_dwordx4 v[248:251], v239, s[80:81]
	global_load_dwordx4 v[24:27], v246, s[72:73]
	global_load_dwordx4 v[28:31], v247, s[72:73]
	s_waitcnt lgkmcnt(0)
	s_waitcnt vmcnt(37)
	v_mfma_f32_16x16x32_bf16 v[100:103], v[100:103], v[8:11], 0
	v_mfma_f32_16x16x32_bf16 v[116:119], v[116:119], v[8:11], 0
	v_mfma_f32_16x16x32_bf16 v[100:103], v[104:107], v[0:3], v[100:103]
	v_mfma_f32_16x16x32_bf16 v[104:107], v[120:123], v[0:3], v[116:119]
	v_mfma_f32_16x16x32_bf16 v[100:103], v[108:111], v[4:7], v[100:103]
	v_mfma_f32_16x16x32_bf16 v[108:111], v[124:127], v[4:7], v[104:107]
	s_waitcnt vmcnt(36)
	v_mfma_f32_16x16x32_bf16 v[104:107], v[112:115], v[12:15], v[100:103]
	v_mfma_f32_16x16x32_bf16 v[100:103], v[128:131], v[12:15], v[108:111]
	ds_read_b128 v[108:111], v177 offset:8192
	ds_read_b128 v[112:115], v191 offset:8192
	ds_read_b128 v[116:119], v163 offset:8192
	ds_read_b128 v[120:123], v164 offset:8192
	ds_read_b128 v[124:127], v177 offset:12288
	ds_read_b128 v[128:131], v191 offset:12288
	ds_read_b128 v[132:135], v163 offset:12288
	ds_read_b128 v[136:139], v164 offset:12288
	s_waitcnt lgkmcnt(0)
	s_nop 4
	v_mfma_f32_16x16x32_bf16 v[108:111], v[108:111], v[8:11], 0
	s_add_i32 s8, s17, 0xffffff56
	s_cmp_lt_u32 s8, 0xfffffefd
	v_mfma_f32_16x16x32_bf16 v[108:111], v[112:115], v[0:3], v[108:111]
	v_mfma_f32_16x16x32_bf16 v[124:127], v[124:127], v[8:11], 0
	v_mfma_f32_16x16x32_bf16 v[108:111], v[116:119], v[4:7], v[108:111]
	ds_read_b64_tr_b16 v[116:117], v172 offset:0
	ds_read_b64_tr_b16 v[118:119], v172 offset:8192
	v_mfma_f32_16x16x32_bf16 v[112:115], v[128:131], v[0:3], v[124:127]
	v_mfma_f32_16x16x32_bf16 v[128:131], v[120:123], v[12:15], v[108:111]
	ds_read_b64_tr_b16 v[108:109], v172 offset:16384
	ds_read_b64_tr_b16 v[110:111], v172 offset:24576
	ds_read_b64_tr_b16 v[120:121], v175 offset:0
	v_mfma_f32_16x16x32_bf16 v[112:115], v[132:135], v[4:7], v[112:115]
	ds_read_b64_tr_b16 v[122:123], v175 offset:8192
	ds_read_b64_tr_b16 v[124:125], v175 offset:16384
	ds_read_b64_tr_b16 v[126:127], v175 offset:24576
	v_mfma_f32_16x16x32_bf16 v[112:115], v[136:139], v[12:15], v[112:115]
	ds_read_b64_tr_b16 v[136:137], v176 offset:0
	ds_read_b64_tr_b16 v[138:139], v176 offset:8192
	ds_read_b64_tr_b16 v[132:133], v176 offset:16384
	ds_read_b64_tr_b16 v[134:135], v176 offset:24576
	ds_read_b64_tr_b16 v[140:141], v181 offset:0
	ds_read_b64_tr_b16 v[142:143], v181 offset:8192
	ds_read_b64_tr_b16 v[144:145], v181 offset:16384
	ds_read_b64_tr_b16 v[146:147], v181 offset:24576
	s_cbranch_scc1 .LBB0_254
	v_add3_u32 v152, v193, s17, 64
	v_max_i32_e32 v67, -1, v152
	v_add_u32_e32 v67, 1, v67
	v_med3_i32 v66, v152, 0, v188
	s_add_i32 s8, 0, 0x1a800
	v_min_u32_e32 v67, 0x100, v67
	v_lshl_add_u32 v66, v66, 2, s8
	v_lshl_add_u32 v67, v67, 2, s8
	ds_read_b32 v66, v66
	ds_read_b32 v67, v67
	v_max_i32_e32 v153, -2, v152
	v_add_u32_e32 v153, 2, v153
	v_min_u32_e32 v153, 0x100, v153
	v_lshl_add_u32 v153, v153, 2, s8
	ds_read_b32 v224, v153
	v_max_i32_e32 v153, -3, v152
	s_waitcnt lgkmcnt(1)
	v_pk_add_f32 v[104:105], v[104:105], v[66:67]
	v_max_i32_e32 v66, -16, v152
	v_max_i32_e32 v67, 0xffffffef, v152
	v_add_u32_e32 v153, 3, v153
	v_add_u32_e32 v66, 16, v66
	v_add_u32_e32 v67, 17, v67
	v_min_u32_e32 v153, 0x100, v153
	v_min_u32_e32 v66, 0x100, v66
	v_min_u32_e32 v67, 0x100, v67
	v_lshl_add_u32 v153, v153, 2, s8
	v_lshl_add_u32 v66, v66, 2, s8
	v_lshl_add_u32 v67, v67, 2, s8
	ds_read_b32 v225, v153
	ds_read_b32 v66, v66
	ds_read_b32 v67, v67
	v_max_i32_e32 v153, 0xffffffee, v152
	v_add_u32_e32 v153, 18, v153
	v_min_u32_e32 v153, 0x100, v153
	v_lshl_add_u32 v153, v153, 2, s8
	s_waitcnt lgkmcnt(0)
	v_pk_add_f32 v[100:101], v[100:101], v[66:67]
	v_max_i32_e32 v66, 0xffffffe0, v152
	v_max_i32_e32 v67, 0xffffffdf, v152
	v_add_u32_e32 v66, 32, v66
	v_add_u32_e32 v67, 33, v67
	v_min_u32_e32 v66, 0x100, v66
	v_min_u32_e32 v67, 0x100, v67
	v_lshl_add_u32 v66, v66, 2, s8
	v_lshl_add_u32 v67, v67, 2, s8
	v_pk_add_f32 v[106:107], v[106:107], v[224:225]
	ds_read_b32 v224, v153
	ds_read_b32 v66, v66
	ds_read_b32 v67, v67
	v_max_i32_e32 v153, 0xffffffed, v152
	v_add_u32_e32 v153, 19, v153
	v_min_u32_e32 v153, 0x100, v153
	v_lshl_add_u32 v153, v153, 2, s8
	ds_read_b32 v225, v153
	v_max_i32_e32 v153, 0xffffffde, v152
	v_add_u32_e32 v153, 34, v153
	v_min_u32_e32 v153, 0x100, v153
	v_lshl_add_u32 v153, v153, 2, s8
	s_waitcnt lgkmcnt(0)
	v_pk_add_f32 v[102:103], v[102:103], v[224:225]
	ds_read_b32 v224, v153
	v_max_i32_e32 v153, 0xffffffdd, v152
	v_add_u32_e32 v153, 35, v153
	v_min_u32_e32 v153, 0x100, v153
	v_lshl_add_u32 v153, v153, 2, s8
	ds_read_b32 v225, v153
	v_pk_add_f32 v[128:129], v[128:129], v[66:67]
	v_max_i32_e32 v66, 0xffffffd0, v152
	v_max_i32_e32 v67, 0xffffffcf, v152
	v_max_i32_e32 v153, 0xffffffce, v152
	v_max_i32_e32 v152, 0xffffffcd, v152
	v_add_u32_e32 v66, 48, v66
	v_add_u32_e32 v67, 49, v67
	v_add_u32_e32 v153, 50, v153
	v_add_u32_e32 v152, 51, v152
	v_min_u32_e32 v66, 0x100, v66
	v_min_u32_e32 v67, 0x100, v67
	v_min_u32_e32 v153, 0x100, v153
	v_min_u32_e32 v152, 0x100, v152
	v_lshl_add_u32 v66, v66, 2, s8
	v_lshl_add_u32 v67, v67, 2, s8
	v_lshl_add_u32 v153, v153, 2, s8
	v_lshl_add_u32 v152, v152, 2, s8
	s_waitcnt lgkmcnt(0)
	v_pk_add_f32 v[130:131], v[130:131], v[224:225]
	ds_read_b32 v66, v66
	ds_read_b32 v67, v67
	ds_read_b32 v224, v153
	ds_read_b32 v225, v152
	s_waitcnt lgkmcnt(2)
	v_pk_add_f32 v[112:113], v[112:113], v[66:67]
	s_waitcnt lgkmcnt(0)
	v_pk_add_f32 v[114:115], v[114:115], v[224:225]

.LBB0_256:
	v_sub_f32_e32 v66, v66, v221
	v_mul_f32_e32 v66, 0x3e0293ee, v66
	v_fmamk_f32 v67, v104, 0x3e0293ee, v66
	v_exp_f32_e32 v223, v67
	v_fmamk_f32 v67, v105, 0x3e0293ee, v66
	v_exp_f32_e32 v224, v67
	v_fmamk_f32 v67, v106, 0x3e0293ee, v66
	v_exp_f32_e32 v225, v67
	v_fmamk_f32 v67, v107, 0x3e0293ee, v66
	v_exp_f32_e32 v226, v67
	v_fmamk_f32 v67, v100, 0x3e0293ee, v66
	v_exp_f32_e32 v227, v67
	v_fmamk_f32 v67, v101, 0x3e0293ee, v66
	v_exp_f32_e32 v228, v67
	v_fmamk_f32 v67, v102, 0x3e0293ee, v66
	v_exp_f32_e32 v229, v67
	v_fmamk_f32 v67, v103, 0x3e0293ee, v66
	v_exp_f32_e32 v230, v67
	v_fmamk_f32 v67, v128, 0x3e0293ee, v66
	v_exp_f32_e32 v231, v67
	v_fmamk_f32 v67, v129, 0x3e0293ee, v66
	v_exp_f32_e32 v232, v67
	v_fmamk_f32 v67, v130, 0x3e0293ee, v66
	v_exp_f32_e32 v233, v67
	v_fmamk_f32 v67, v131, 0x3e0293ee, v66
	v_exp_f32_e32 v234, v67
	v_fmamk_f32 v67, v112, 0x3e0293ee, v66
	v_exp_f32_e32 v235, v67
	v_fmamk_f32 v67, v113, 0x3e0293ee, v66
	v_exp_f32_e32 v236, v67
	v_fmamk_f32 v67, v114, 0x3e0293ee, v66
	v_fmac_f32_e32 v66, 0x3e0293ee, v115
	v_exp_f32_e32 v237, v67
	v_exp_f32_e32 v238, v66
	s_waitcnt lgkmcnt(0)
	s_add_i32 s8, s0, 2
	v_cvt_pk_bf16_f32 v104, v223, v224
	v_cvt_pk_bf16_f32 v105, v225, v226
	v_cvt_pk_bf16_f32 v106, v227, v228
	v_cvt_pk_bf16_f32 v107, v229, v230
	v_cvt_pk_bf16_f32 v100, v231, v232
	v_cvt_pk_bf16_f32 v101, v233, v234
	v_cvt_pk_bf16_f32 v102, v235, v236
	v_cvt_pk_bf16_f32 v103, v237, v238
	v_mfma_f32_16x16x32_bf16 v[96:99], v[116:119], v[104:107], v[96:99]
	s_nop 0
	v_mfma_f32_16x16x32_bf16 v[96:99], v[108:111], v[100:103], v[96:99]
	ds_read_b64_tr_b16 v[108:109], v218 offset:0
	ds_read_b64_tr_b16 v[110:111], v218 offset:8192
	ds_read_b64_tr_b16 v[112:113], v218 offset:16384
	ds_read_b64_tr_b16 v[114:115], v218 offset:24576
	v_mfma_f32_16x16x32_bf16 v[88:91], v[120:123], v[104:107], v[88:91]
	ds_read_b64_tr_b16 v[116:117], v219 offset:0
	ds_read_b64_tr_b16 v[118:119], v219 offset:8192
	ds_read_b64_tr_b16 v[120:121], v219 offset:16384
	ds_read_b64_tr_b16 v[122:123], v219 offset:24576
	v_mfma_f32_16x16x32_bf16 v[80:83], v[136:139], v[104:107], v[80:83]
	v_mfma_f32_16x16x32_bf16 v[88:91], v[124:127], v[100:103], v[88:91]
	ds_read_b64_tr_b16 v[124:125], v220 offset:0
	ds_read_b64_tr_b16 v[126:127], v220 offset:8192
	ds_read_b64_tr_b16 v[128:129], v220 offset:16384
	v_mfma_f32_16x16x32_bf16 v[72:75], v[140:143], v[104:107], v[72:75]
	ds_read_b64_tr_b16 v[130:131], v220 offset:24576
	v_mfma_f32_16x16x32_bf16 v[80:83], v[132:135], v[100:103], v[80:83]
	ds_read_b64_tr_b16 v[132:133], v171 offset:0
	ds_read_b64_tr_b16 v[134:135], v171 offset:8192
	ds_read_b64_tr_b16 v[136:137], v171 offset:16384
	v_mfma_f32_16x16x32_bf16 v[72:75], v[144:147], v[100:103], v[72:75]
	ds_read_b64_tr_b16 v[138:139], v171 offset:24576
	s_waitcnt lgkmcnt(0)
	v_mfma_f32_16x16x32_bf16 v[56:59], v[108:111], v[104:107], v[56:59]
	ds_read_b64_tr_b16 v[108:109], v172 offset:256
	ds_read_b64_tr_b16 v[110:111], v172 offset:8448
	v_mfma_f32_16x16x32_bf16 v[48:51], v[116:119], v[104:107], v[48:51]
	v_mfma_f32_16x16x32_bf16 v[56:59], v[112:115], v[100:103], v[56:59]
	ds_read_b64_tr_b16 v[112:113], v172 offset:16640
	ds_read_b64_tr_b16 v[114:115], v172 offset:24832
	ds_read_b64_tr_b16 v[116:117], v175 offset:256
	ds_read_b64_tr_b16 v[118:119], v175 offset:8448
	v_mfma_f32_16x16x32_bf16 v[40:43], v[124:127], v[104:107], v[40:43]
	v_mfma_f32_16x16x32_bf16 v[48:51], v[120:123], v[100:103], v[48:51]
	ds_read_b64_tr_b16 v[120:121], v175 offset:16640
	ds_read_b64_tr_b16 v[122:123], v175 offset:24832
	ds_read_b64_tr_b16 v[124:125], v176 offset:256
	ds_read_b64_tr_b16 v[126:127], v176 offset:8448
	v_mfma_f32_16x16x32_bf16 v[32:35], v[132:135], v[104:107], v[32:35]
	v_mfma_f32_16x16x32_bf16 v[40:43], v[128:131], v[100:103], v[40:43]
	ds_read_b64_tr_b16 v[128:129], v176 offset:16640
	ds_read_b64_tr_b16 v[130:131], v176 offset:24832
	ds_read_b64_tr_b16 v[132:133], v181 offset:256
	ds_read_b64_tr_b16 v[134:135], v181 offset:8448
	v_mfma_f32_16x16x32_bf16 v[32:35], v[136:139], v[100:103], v[32:35]
	ds_read_b64_tr_b16 v[136:137], v181 offset:16640
	ds_read_b64_tr_b16 v[138:139], v181 offset:24832
	s_waitcnt lgkmcnt(0)
	v_mfma_f32_16x16x32_bf16 v[92:95], v[108:111], v[104:107], v[92:95]
	ds_read_b64_tr_b16 v[108:109], v218 offset:256
	ds_read_b64_tr_b16 v[110:111], v218 offset:8448
	v_mfma_f32_16x16x32_bf16 v[84:87], v[116:119], v[104:107], v[84:87]
	v_mfma_f32_16x16x32_bf16 v[92:95], v[112:115], v[100:103], v[92:95]
	ds_read_b64_tr_b16 v[112:113], v218 offset:16640
	ds_read_b64_tr_b16 v[114:115], v218 offset:24832
	ds_read_b64_tr_b16 v[116:117], v219 offset:256
	ds_read_b64_tr_b16 v[118:119], v219 offset:8448
	v_mfma_f32_16x16x32_bf16 v[76:79], v[124:127], v[104:107], v[76:79]
	v_mfma_f32_16x16x32_bf16 v[84:87], v[120:123], v[100:103], v[84:87]
	ds_read_b64_tr_b16 v[120:121], v219 offset:16640
	ds_read_b64_tr_b16 v[122:123], v219 offset:24832
	ds_read_b64_tr_b16 v[124:125], v220 offset:256
	ds_read_b64_tr_b16 v[126:127], v220 offset:8448
	v_mfma_f32_16x16x32_bf16 v[66:69], v[132:135], v[104:107], v[68:71]
	v_mfma_f32_16x16x32_bf16 v[76:79], v[128:131], v[100:103], v[76:79]
	ds_read_b64_tr_b16 v[128:129], v220 offset:16640
	ds_read_b64_tr_b16 v[130:131], v220 offset:24832
	ds_read_b64_tr_b16 v[132:133], v171 offset:256
	ds_read_b64_tr_b16 v[134:135], v171 offset:8448
	v_mfma_f32_16x16x32_bf16 v[66:69], v[136:139], v[100:103], v[66:69]
	ds_read_b64_tr_b16 v[136:137], v171 offset:16640
	ds_read_b64_tr_b16 v[138:139], v171 offset:24832
	s_waitcnt lgkmcnt(0)
	v_mfma_f32_16x16x32_bf16 v[60:63], v[108:111], v[104:107], v[60:63]
	s_waitcnt vmcnt(6)
	ds_write_b128 v166, v[16:19] offset:17408
	v_mfma_f32_16x16x32_bf16 v[52:55], v[116:119], v[104:107], v[52:55]
	ds_write_b128 v167, v[20:23] offset:17408
	v_mfma_f32_16x16x32_bf16 v[44:47], v[124:127], v[104:107], v[44:47]
	ds_write_b128 v169, v[194:197] offset:36864
	v_mfma_f32_16x16x32_bf16 v[36:39], v[132:135], v[104:107], v[36:39]
	ds_write_b128 v169, v[198:201] offset:45056
	v_mfma_f32_16x16x32_bf16 v[60:63], v[112:115], v[100:103], v[60:63]
	ds_write_b128 v169, v[202:205] offset:53248
	v_mfma_f32_16x16x32_bf16 v[52:55], v[120:123], v[100:103], v[52:55]
	ds_write_b128 v169, v[242:245] offset:61440
	v_mfma_f32_16x16x32_bf16 v[44:47], v[128:131], v[100:103], v[44:47]
	v_mfma_f32_16x16x32_bf16 v[36:39], v[136:139], v[100:103], v[36:39]
	s_mov_b32 s9, s8
	s_lshl_b32 s9, s9, 6
	s_addk_i32 s9, 0xc0
	s_mul_i32 s29, s9, 0xa080
	s_add_u32 s72, s24, s29
	s_addc_u32 s73, s25, 0
	s_add_u32 s74, s26, s29
	s_addc_u32 s75, s27, 0
	s_add_u32 s76, s74, 0xa0800
	s_addc_u32 s77, s75, 0
	s_add_u32 s78, s76, 0xa0800
	s_addc_u32 s79, s77, 0
	s_add_u32 s80, s78, 0xa0800
	s_addc_u32 s81, s79, 0
	s_waitcnt lgkmcnt(0)
	s_barrier
	ds_read_b128 v[100:103], v177 offset:17408
	ds_read_b128 v[104:107], v191 offset:17408
	ds_read_b128 v[108:111], v163 offset:17408
	ds_read_b128 v[112:115], v164 offset:17408
	ds_read_b128 v[116:119], v177 offset:21504
	ds_read_b128 v[120:123], v191 offset:21504
	ds_read_b128 v[124:127], v163 offset:21504
	ds_read_b128 v[128:131], v164 offset:21504
	global_load_dwordx4 v[194:197], v239, s[74:75]
	global_load_dwordx4 v[198:201], v239, s[76:77]
	global_load_dwordx4 v[202:205], v239, s[78:79]
	global_load_dwordx4 v[242:245], v239, s[80:81]
	global_load_dwordx4 v[16:19], v246, s[72:73]
	global_load_dwordx4 v[20:23], v247, s[72:73]
	s_waitcnt lgkmcnt(0)
	s_nop 0
	v_mfma_f32_16x16x32_bf16 v[100:103], v[100:103], v[8:11], 0
	v_mfma_f32_16x16x32_bf16 v[116:119], v[116:119], v[8:11], 0
	v_mfma_f32_16x16x32_bf16 v[100:103], v[104:107], v[0:3], v[100:103]
	v_mfma_f32_16x16x32_bf16 v[104:107], v[120:123], v[0:3], v[116:119]
	v_mfma_f32_16x16x32_bf16 v[100:103], v[108:111], v[4:7], v[100:103]
	v_mfma_f32_16x16x32_bf16 v[104:107], v[124:127], v[4:7], v[104:107]
	v_mfma_f32_16x16x32_bf16 v[112:115], v[112:115], v[12:15], v[100:103]
	v_mfma_f32_16x16x32_bf16 v[100:103], v[128:131], v[12:15], v[104:107]
	ds_read_b128 v[104:107], v177 offset:25600
	ds_read_b128 v[108:111], v191 offset:25600
	ds_read_b128 v[116:119], v163 offset:25600
	ds_read_b128 v[120:123], v164 offset:25600
	ds_read_b128 v[124:127], v177 offset:29696
	ds_read_b128 v[128:131], v191 offset:29696
	ds_read_b128 v[132:135], v163 offset:29696
	ds_read_b128 v[136:139], v164 offset:29696
	s_waitcnt lgkmcnt(0)
	s_nop 5
	v_mfma_f32_16x16x32_bf16 v[104:107], v[104:107], v[8:11], 0
	s_add_i32 s9, s17, 0xffffff96
	s_cmp_lt_u32 s9, 0xfffffefd
	v_mfma_f32_16x16x32_bf16 v[104:107], v[108:111], v[0:3], v[104:107]
	v_mfma_f32_16x16x32_bf16 v[124:127], v[124:127], v[8:11], 0
	v_mfma_f32_16x16x32_bf16 v[104:107], v[116:119], v[4:7], v[104:107]
	ds_read_b64_tr_b16 v[116:117], v172 offset:36864
	ds_read_b64_tr_b16 v[118:119], v172 offset:45056
	v_mfma_f32_16x16x32_bf16 v[108:111], v[128:131], v[0:3], v[124:127]
	v_mfma_f32_16x16x32_bf16 v[128:131], v[120:123], v[12:15], v[104:107]
	ds_read_b64_tr_b16 v[104:105], v172 offset:53248
	ds_read_b64_tr_b16 v[106:107], v172 offset:61440
	ds_read_b64_tr_b16 v[120:121], v175 offset:36864
	v_mfma_f32_16x16x32_bf16 v[108:111], v[132:135], v[4:7], v[108:111]
	ds_read_b64_tr_b16 v[122:123], v175 offset:45056
	ds_read_b64_tr_b16 v[124:125], v175 offset:53248
	ds_read_b64_tr_b16 v[126:127], v175 offset:61440
	v_mfma_f32_16x16x32_bf16 v[108:111], v[136:139], v[12:15], v[108:111]
	ds_read_b64_tr_b16 v[136:137], v176 offset:36864
	ds_read_b64_tr_b16 v[138:139], v176 offset:45056
	ds_read_b64_tr_b16 v[132:133], v176 offset:53248
	ds_read_b64_tr_b16 v[134:135], v176 offset:61440
	ds_read_b64_tr_b16 v[140:141], v181 offset:36864
	ds_read_b64_tr_b16 v[142:143], v181 offset:45056
	ds_read_b64_tr_b16 v[144:145], v181 offset:53248
	ds_read_b64_tr_b16 v[146:147], v181 offset:61440
	s_cbranch_scc1 .LBB0_258
	v_add_u32_e32 v70, s17, v193
	v_add_u32_e32 v152, 0x80, v70
	v_max_i32_e32 v71, -1, v152
	v_add_u32_e32 v71, 1, v71
	v_med3_i32 v70, v152, 0, v188
	s_add_i32 s9, 0, 0x1a800
	v_min_u32_e32 v71, 0x100, v71
	v_lshl_add_u32 v70, v70, 2, s9
	v_lshl_add_u32 v71, v71, 2, s9
	ds_read_b32 v70, v70
	ds_read_b32 v71, v71
	v_max_i32_e32 v153, -2, v152
	v_add_u32_e32 v153, 2, v153
	v_min_u32_e32 v153, 0x100, v153
	v_lshl_add_u32 v153, v153, 2, s9
	ds_read_b32 v240, v153
	v_max_i32_e32 v153, -3, v152
	s_waitcnt lgkmcnt(1)
	v_pk_add_f32 v[112:113], v[112:113], v[70:71]
	v_max_i32_e32 v70, -16, v152
	v_max_i32_e32 v71, 0xffffffef, v152
	v_add_u32_e32 v153, 3, v153
	v_add_u32_e32 v70, 16, v70
	v_add_u32_e32 v71, 17, v71
	v_min_u32_e32 v153, 0x100, v153
	v_min_u32_e32 v70, 0x100, v70
	v_min_u32_e32 v71, 0x100, v71
	v_lshl_add_u32 v153, v153, 2, s9
	v_lshl_add_u32 v70, v70, 2, s9
	v_lshl_add_u32 v71, v71, 2, s9
	ds_read_b32 v241, v153
	ds_read_b32 v70, v70
	ds_read_b32 v71, v71
	v_max_i32_e32 v153, 0xffffffee, v152
	v_add_u32_e32 v153, 18, v153
	v_min_u32_e32 v153, 0x100, v153
	v_lshl_add_u32 v153, v153, 2, s9
	s_waitcnt lgkmcnt(0)
	v_pk_add_f32 v[100:101], v[100:101], v[70:71]
	v_max_i32_e32 v70, 0xffffffe0, v152
	v_max_i32_e32 v71, 0xffffffdf, v152
	v_add_u32_e32 v70, 32, v70
	v_add_u32_e32 v71, 33, v71
	v_min_u32_e32 v70, 0x100, v70
	v_min_u32_e32 v71, 0x100, v71
	v_lshl_add_u32 v70, v70, 2, s9
	v_lshl_add_u32 v71, v71, 2, s9
	v_pk_add_f32 v[114:115], v[114:115], v[240:241]
	ds_read_b32 v240, v153
	ds_read_b32 v70, v70
	ds_read_b32 v71, v71
	v_max_i32_e32 v153, 0xffffffed, v152
	v_add_u32_e32 v153, 19, v153
	v_min_u32_e32 v153, 0x100, v153
	v_lshl_add_u32 v153, v153, 2, s9
	ds_read_b32 v241, v153
	v_max_i32_e32 v153, 0xffffffde, v152
	v_add_u32_e32 v153, 34, v153
	v_min_u32_e32 v153, 0x100, v153
	v_lshl_add_u32 v153, v153, 2, s9
	s_waitcnt lgkmcnt(0)
	v_pk_add_f32 v[102:103], v[102:103], v[240:241]
	ds_read_b32 v240, v153
	v_max_i32_e32 v153, 0xffffffdd, v152
	v_add_u32_e32 v153, 35, v153
	v_min_u32_e32 v153, 0x100, v153
	v_lshl_add_u32 v153, v153, 2, s9
	ds_read_b32 v241, v153
	v_pk_add_f32 v[128:129], v[128:129], v[70:71]
	v_max_i32_e32 v70, 0xffffffd0, v152
	v_max_i32_e32 v71, 0xffffffcf, v152
	v_max_i32_e32 v153, 0xffffffce, v152
	v_max_i32_e32 v152, 0xffffffcd, v152
	v_add_u32_e32 v70, 48, v70
	v_add_u32_e32 v71, 49, v71
	v_add_u32_e32 v153, 50, v153
	v_add_u32_e32 v152, 51, v152
	v_min_u32_e32 v70, 0x100, v70
	v_min_u32_e32 v71, 0x100, v71
	v_min_u32_e32 v153, 0x100, v153
	v_min_u32_e32 v152, 0x100, v152
	v_lshl_add_u32 v70, v70, 2, s9
	v_lshl_add_u32 v71, v71, 2, s9
	v_lshl_add_u32 v153, v153, 2, s9
	v_lshl_add_u32 v152, v152, 2, s9
	s_waitcnt lgkmcnt(0)
	v_pk_add_f32 v[130:131], v[130:131], v[240:241]
	ds_read_b32 v70, v70
	ds_read_b32 v71, v71
	ds_read_b32 v240, v153
	ds_read_b32 v241, v152
	s_waitcnt lgkmcnt(2)
	v_pk_add_f32 v[108:109], v[108:109], v[70:71]
	s_waitcnt lgkmcnt(0)
	v_pk_add_f32 v[110:111], v[110:111], v[240:241]
